# Wg conversion also moved out of the prologue (FFN1-in idle slot of the same layer); prologue keeps only W1in of layer 0 and the x cast
# speedup vs baseline: 1.0037x; 1.0004x over previous
.LBB0_9:
	s_lshl_b32 s2, 1, s28
	s_and_b32 s2, s2, 1
	s_cmp_eq_u32 s2, 0
	s_cbranch_scc1 .LBB0_8
	s_mov_b32 s2, s33
	s_cmp_lt_i32 s28, 2
	s_waitcnt vmcnt(0)
	v_mov_b32_e32 v2, s2
	ds_read2_b32 v[2:3], v2 offset1:1
	s_mov_b64 s[14:15], -1
	s_waitcnt lgkmcnt(0)
	v_readfirstlane_b32 s16, v2
	v_readfirstlane_b32 s17, v3
	s_cbranch_scc1 .LBB0_35
	s_cmp_lt_i32 s28, 3
	s_cbranch_scc1 .LBB0_32
	s_cmp_lg_u32 s28, 3
	s_cbranch_scc0 .LBB0_29
	s_cmp_gt_u32 s28, 7
	s_cbranch_scc0 .LBB0_26
	s_cmp_lt_i32 s28, 9
	s_cbranch_scc1 .LBB0_23
	s_cmp_lt_i32 s28, 10
	s_mov_b64 s[12:13], -1
	s_cbranch_scc1 .LBB0_21
	s_cmp_lg_u32 s28, 10
	s_mov_b64 s[10:11], -1
	s_cbranch_scc0 .LBB0_18
	v_readlane_b32 s2, v254, 0
	s_add_i32 s6, s28, -11
	s_mov_b64 s[10:11], 0
	v_mov_b32_e32 v2, s2
	ds_read2_b32 v[2:3], v2 offset1:1
	s_lshl_b64 s[2:3], s[6:7], 21
	s_waitcnt lgkmcnt(0)
	v_readfirstlane_b32 s8, v2
	v_readfirstlane_b32 s9, v3
	s_add_u32 s8, s8, s2
	s_addc_u32 s9, s9, s3
	s_lshl_b64 s[2:3], s[6:7], 20
	s_add_u32 s2, s16, s2
	s_addc_u32 s3, s17, s3
	s_add_u32 s2, s2, 0x3380000
	s_addc_u32 s3, s3, 0

.LBB0_414:
	s_lshl_b32 s0, 1, s24
	s_and_b32 s0, s0, 0x20e
	s_cmp_eq_u32 s0, 0
	s_cbranch_scc1 .LBB0_413
	s_mov_b32 s0, s33
	s_mov_b64 s[16:17], -1
	v_mov_b32_e32 v0, s0
	ds_read2_b32 v[2:3], v0 offset1:1
	s_waitcnt lgkmcnt(0)
	v_readfirstlane_b32 s0, v2
	v_readfirstlane_b32 s1, v3
	s_add_u32 s0, s0, s54
	s_addc_u32 s1, s1, 0
	s_add_u32 s14, s0, 0x100000
	s_addc_u32 s15, s1, 0
	s_cmp_lt_i32 s24, 2
	s_cbranch_scc1 .LBB0_440
	s_cmp_lt_i32 s24, 3
	s_cbranch_scc1 .LBB0_437
	s_cmp_lg_u32 s24, 3
	s_cbranch_scc0 .LBB0_434
	s_cmp_gt_u32 s24, 7
	s_cbranch_scc0 .LBB0_431
	s_cmp_lt_i32 s24, 9
	s_cbranch_scc1 .LBB0_428
	s_cmp_lt_i32 s24, 10
	s_mov_b64 s[10:11], -1
	s_cbranch_scc1 .LBB0_426
	s_cmp_lg_u32 s24, 10
	s_mov_b64 s[8:9], -1
	s_cbranch_scc0 .LBB0_423
	v_readlane_b32 s0, v254, 0
	s_add_i32 s94, s24, -11
	s_mov_b64 s[8:9], 0
	v_mov_b32_e32 v0, s0
	ds_read2_b32 v[2:3], v0 offset1:1
	s_waitcnt lgkmcnt(0)
	v_readfirstlane_b32 s0, v2
	v_readfirstlane_b32 s1, v3
	s_add_u32 s6, s0, s4
	s_addc_u32 s7, s1, s5
	s_lshl_b64 s[0:1], s[94:95], 21
	s_add_u32 s6, s6, s0
	s_addc_u32 s7, s7, s1
	s_lshl_b64 s[0:1], s[94:95], 20
	s_add_u32 s0, s14, s0
	s_addc_u32 s1, s15, s1
	s_add_u32 s0, s0, 0x3280000
	s_addc_u32 s1, s1, 0

.LBB0_2087:
	s_lshl_b32 s2, 1, s24
	s_and_b32 s2, s2, 1
	s_cmp_eq_u32 s2, 0
	s_cbranch_scc1 .LBB0_2086
	s_mov_b32 s2, s33
	s_cmp_lt_i32 s24, 2
	v_mov_b32_e32 v0, s2
	ds_read2_b32 v[2:3], v0 offset1:1
	s_mov_b64 s[14:15], -1
	s_waitcnt lgkmcnt(0)
	v_readfirstlane_b32 s16, v2
	v_readfirstlane_b32 s17, v3
	s_cbranch_scc1 .LBB0_2113
	s_cmp_lt_i32 s24, 3
	s_cbranch_scc1 .LBB0_2110
	s_cmp_lg_u32 s24, 3
	s_cbranch_scc0 .LBB0_2107
	s_cmp_gt_u32 s24, 7
	s_cbranch_scc0 .LBB0_2104
	s_cmp_lt_i32 s24, 9
	s_cbranch_scc1 .LBB0_2101
	s_cmp_lt_i32 s24, 10
	s_mov_b64 s[12:13], -1
	s_cbranch_scc1 .LBB0_2099
	s_cmp_lg_u32 s24, 10
	s_mov_b64 s[6:7], -1
	s_cbranch_scc0 .LBB0_2096
	v_readlane_b32 s2, v254, 0
	s_add_i32 s94, s24, -11
	s_mov_b64 s[6:7], 0
	v_mov_b32_e32 v0, s2
	ds_read2_b32 v[2:3], v0 offset1:1
	s_lshl_b64 s[2:3], s[94:95], 21
	s_waitcnt lgkmcnt(0)
	v_readfirstlane_b32 s4, v2
	v_readfirstlane_b32 s5, v3
	s_add_u32 s2, s4, s2
	s_addc_u32 s3, s5, s3
	s_add_u32 s4, s2, 0x400000
	s_addc_u32 s5, s3, 0
	s_lshl_b64 s[2:3], s[94:95], 20
	s_add_u32 s2, s16, s2
	s_addc_u32 s3, s17, s3
	s_add_u32 s2, s2, 0x6800000
	s_addc_u32 s3, s3, 0
